# attention: tile DMA issue moved behind the QK MFMAs on two-row tiles; interleaved chains; bias table in LDS
# speedup vs baseline: 1.0021x; 1.0021x over previous
.Lat_wdone:
	s_barrier
	s_cmp_lt_u32 s71, s78
	s_cbranch_scc0 .Lat_ctx_tile
	s_add_i32 s27, s32, s71
	s_sub_i32 s70, s27, s15
	s_cmp_lt_u32 s70, s2
	s_cselect_b32 s100, 1, 0
	s_cbranch_scc0 .Lat_loc_dma
	v_add_u32_e32 v247, 32, v188
	v_med3_i32 v247, v247, 0, s22
	ds_read_b32 v213, v247
	v_add_u32_e32 v248, 36, v188
	v_med3_i32 v248, v248, 0, s22
	ds_read_b32 v214, v248
	v_add_u32_e32 v247, 40, v188
	v_med3_i32 v247, v247, 0, s22
	ds_read_b32 v215, v247
	v_add_u32_e32 v248, 44, v188
	v_med3_i32 v248, v248, 0, s22
	ds_read_b32 v216, v248
	v_add_u32_e32 v247, 48, v188
	v_med3_i32 v247, v247, 0, s22
	ds_read_b32 v217, v247
	v_add_u32_e32 v248, 52, v188
	v_med3_i32 v248, v248, 0, s22
	ds_read_b32 v218, v248
	v_add_u32_e32 v247, 56, v188
	v_med3_i32 v247, v247, 0, s22
	ds_read_b32 v219, v247
	v_add_u32_e32 v248, 60, v188
	v_med3_i32 v248, v248, 0, s22
	ds_read_b32 v220, v248
	v_subrev_u32_e32 v247, 92, v188
	v_med3_i32 v247, v247, 0, s22
	ds_read_b32 v221, v247
	v_subrev_u32_e32 v248, 88, v188
	v_med3_i32 v248, v248, 0, s22
	ds_read_b32 v222, v248
	v_subrev_u32_e32 v247, 84, v188
	v_med3_i32 v247, v247, 0, s22
	ds_read_b32 v223, v247
	v_subrev_u32_e32 v248, 80, v188
	v_med3_i32 v248, v248, 0, s22
	ds_read_b32 v224, v248
	v_subrev_u32_e32 v247, 76, v188
	v_med3_i32 v247, v247, 0, s22
	ds_read_b32 v225, v247
	v_subrev_u32_e32 v248, 72, v188
	v_med3_i32 v248, v248, 0, s22
	ds_read_b32 v226, v248
	v_subrev_u32_e32 v247, 68, v188
	v_med3_i32 v247, v247, 0, s22
	ds_read_b32 v227, v247
	v_subrev_u32_e32 v248, 64, v188
	v_med3_i32 v248, v248, 0, s22
	ds_read_b32 v228, v248
	s_cmp_lt_u32 s70, 8
	s_cselect_b32 s27, 1, 0
	s_add_i32 s42, s3, s70
	s_cmp_ge_u32 s42, s14
	s_cselect_b32 s42, 1, 0
	s_and_b32 s27, s27, s42
	s_cmp_lg_u32 s27, 0
	s_cbranch_scc0 .Lat_loc_dma
	v_add_u32_e32 v242, s99, v255
	v_xor_b32_e32 v243, 64, v255
	v_xor_b32_e32 v244, 0x80, v255
	v_xor_b32_e32 v245, 0xc0, v255
	v_add_u32_e32 v243, s99, v243
	v_add_u32_e32 v244, s99, v244
	v_add_u32_e32 v245, s99, v245
	v_add_u32_e32 v246, s99, v191
	ds_read_b128 v[142:145], v242
	ds_read_b128 v[130:133], v243
	ds_read_b128 v[134:137], v244
	ds_read_b128 v[138:141], v245
	ds_read_b128 v[158:161], v242 offset:1024
	ds_read_b128 v[150:153], v243 offset:1024
	ds_read_b128 v[154:157], v244 offset:1024
	ds_read_b128 v[146:149], v245 offset:1024
	ds_read_b128 v[126:129], v246
	ds_read_b128 v[122:125], v246 offset:2048
	ds_read_b128 v[118:121], v246 offset:4096
	ds_read_b128 v[114:117], v246 offset:6144
	ds_read_b128 v[110:113], v246 offset:8192
	ds_read_b128 v[106:109], v246 offset:10240
	ds_read_b128 v[102:105], v246 offset:12288
	ds_read_b128 v[98:101], v246 offset:14336
	s_mov_b32 s100, 6
	s_branch .Lat_body

.Lat_ctx_tile:
	s_add_i32 s9, s71, 2
	s_add_i32 s42, s78, 4
	s_cmp_lt_u32 s9, s42
	s_cselect_b32 s100, 4, 0
	s_sub_i32 s27, s71, s78
	s_lshl_b32 s27, s27, 1
	s_add_i32 s70, s2, s27
	v_add_u32_e32 v242, s99, v190
	v_xor_b32_e32 v243, 64, v190
	v_xor_b32_e32 v244, 0x80, v190
	v_xor_b32_e32 v245, 0xc0, v190
	v_add_u32_e32 v243, s99, v243
	v_add_u32_e32 v244, s99, v244
	v_add_u32_e32 v245, s99, v245
	v_add_u32_e32 v246, s99, v181
	ds_read_b128 v[142:145], v242
	ds_read_b128 v[130:133], v243
	ds_read_b128 v[134:137], v244
	ds_read_b128 v[138:141], v245
	ds_read_b128 v[158:161], v242 offset:1024
	ds_read_b128 v[150:153], v243 offset:1024
	ds_read_b128 v[154:157], v244 offset:1024
	ds_read_b128 v[146:149], v245 offset:1024
	ds_read_b128 v[126:129], v246
	ds_read_b128 v[122:125], v246 offset:2048
	ds_read_b128 v[118:121], v246 offset:4096
	ds_read_b128 v[114:117], v246 offset:6144
	ds_read_b128 v[110:113], v246 offset:8192
	ds_read_b128 v[106:109], v246 offset:10240
	ds_read_b128 v[102:105], v246 offset:12288
	ds_read_b128 v[98:101], v246 offset:14336
	s_branch .Lat_body

.Lat_merged:
	s_waitcnt lgkmcnt(8)
	v_mfma_f32_16x16x32_bf16 v[162:165], v[142:145], v[50:53], 0
	v_mfma_f32_16x16x32_bf16 v[162:165], v[130:133], v[54:57], v[162:165]
	v_mfma_f32_16x16x32_bf16 v[162:165], v[134:137], v[58:61], v[162:165]
	v_mfma_f32_16x16x32_bf16 v[166:169], v[138:141], v[66:69], v[162:165]
	v_mfma_f32_16x16x32_bf16 v[162:165], v[158:161], v[50:53], 0
	v_mfma_f32_16x16x32_bf16 v[162:165], v[150:153], v[54:57], v[162:165]
	v_mfma_f32_16x16x32_bf16 v[162:165], v[154:157], v[58:61], v[162:165]
	v_mfma_f32_16x16x32_bf16 v[162:165], v[146:149], v[66:69], v[162:165]
	v_mfma_f32_16x16x32_bf16 v[142:145], v[142:145], v[78:81], 0
	v_mfma_f32_16x16x32_bf16 v[130:133], v[130:133], v[82:85], v[142:145]
	v_mfma_f32_16x16x32_bf16 v[130:133], v[134:137], v[86:89], v[130:133]
	v_mfma_f32_16x16x32_bf16 v[134:137], v[138:141], v[94:97], v[130:133]
	v_mfma_f32_16x16x32_bf16 v[130:133], v[158:161], v[78:81], 0
	v_mfma_f32_16x16x32_bf16 v[130:133], v[150:153], v[82:85], v[130:133]
	v_mfma_f32_16x16x32_bf16 v[130:133], v[154:157], v[86:89], v[130:133]
	v_mfma_f32_16x16x32_bf16 v[130:133], v[146:149], v[94:97], v[130:133]
	s_bitcmp1_b32 s100, 2
	s_cbranch_scc0 .Lat_m_nodma
	s_and_b32 s100, s100, 3
	s_add_i32 s9, s71, 2
	s_sub_i32 s27, s9, s78
	s_lshr_b32 s42, s23, 9
	s_lshl_b32 s101, s42, 2
	s_add_i32 s27, s27, s101
	s_add_i32 s27, s27, 0x100
	s_lshl_b32 s42, s42, 5
	s_add_i32 s42, s42, s32
	s_add_i32 s42, s42, s9
	s_cmp_lt_u32 s9, s78
	s_cselect_b32 s27, s42, s27
	s_lshl_b32 s27, s27, 6
	s_mul_i32 s42, s27, s37
	s_add_u32 s10, s50, s42
	s_addc_u32 s11, s51, 0
	s_lshl_b32 s101, s13, 1
	s_add_i32 s101, s101, 0x2800
	s_add_u32 s10, s10, s101
	s_addc_u32 s11, s11, 0
	s_lshl_b32 s8, s12, 10
	s_add_i32 s8, s8, s98
	s_mov_b32 m0, s8
	s_add_i32 s8, s8, 0x2000
	global_load_lds_dwordx4 v229, s[10:11]
	s_mov_b32 m0, s8
	s_add_u32 s10, s10, 0xd0000
	s_addc_u32 s11, s11, 0
	global_load_lds_dwordx4 v229, s[10:11]
	v_readlane_b32 s10, v252, 55
	v_readlane_b32 s11, v252, 56
	s_mul_i32 s42, s13, 0x9000
	s_lshl_b32 s101, s27, 1
	s_add_i32 s42, s42, s101
	s_add_i32 s8, s8, 0x2000
	s_add_u32 s10, s10, s42
	s_addc_u32 s11, s11, 0
	s_mov_b32 m0, s8
	s_add_i32 s8, s8, 0x2000
	global_load_lds_dwordx4 v254, s[10:11]
	s_mov_b32 m0, s8
	s_add_u32 s10, s10, 0x240000
	s_addc_u32 s11, s11, 0
	global_load_lds_dwordx4 v254, s[10:11]
	s_add_i32 s98, s98, 0x8000
	s_cmp_eq_u32 s98, 0x19000
	s_cselect_b32 s98, 0x1000, s98
.Lat_m_nodma:
	s_cmp_ge_i32 s70, s2
	s_cbranch_scc1 .Lat_merged_ctx
	s_nop 7
	v_add_f32_e32 v208, v166, v213
	v_add_f32_e32 v140, v134, v221
	v_add_f32_e32 v206, v167, v214
	v_add_f32_e32 v138, v135, v222
	v_add_f32_e32 v209, v168, v215
	v_add_f32_e32 v141, v136, v223
	v_add_f32_e32 v207, v169, v216
	v_add_f32_e32 v139, v137, v224
	v_add_f32_e32 v211, v162, v217
	v_add_f32_e32 v143, v130, v225
	v_add_f32_e32 v210, v163, v218
	v_add_f32_e32 v142, v131, v226
	v_add_f32_e32 v212, v164, v219
	v_add_f32_e32 v145, v132, v227
	v_add_f32_e32 v189, v165, v220
	v_add_f32_e32 v144, v133, v228
	v_cndmask_b32_e64 v208, v253, v208, s[40:41]
	v_cndmask_b32_e64 v140, v253, v140, s[40:41]
	v_cndmask_b32_e64 v206, v253, v206, s[52:53]
	v_cndmask_b32_e64 v138, v253, v138, s[52:53]
	v_cndmask_b32_e64 v209, v253, v209, s[54:55]
	v_cndmask_b32_e64 v141, v253, v141, s[54:55]
	v_cndmask_b32_e64 v207, v253, v207, s[60:61]
	v_cndmask_b32_e64 v139, v253, v139, s[60:61]
	v_cndmask_b32_e64 v211, v253, v211, s[62:63]
	v_cndmask_b32_e64 v143, v253, v143, s[62:63]
	v_cndmask_b32_e64 v210, v253, v210, s[80:81]
	v_cndmask_b32_e64 v142, v253, v142, s[80:81]
	v_cndmask_b32_e64 v212, v253, v212, s[82:83]
	v_cndmask_b32_e64 v145, v253, v145, s[82:83]
	v_cndmask_b32_e64 v189, v253, v189, s[6:7]
	v_cndmask_b32_e64 v144, v253, v144, s[6:7]
	v_max3_f32 v162, v206, v208, v207
	v_max3_f32 v130, v138, v140, v139
	v_max3_f32 v163, v209, v189, v212
	v_max3_f32 v131, v141, v144, v145
	v_max_f32_e32 v164, v211, v210
	v_max_f32_e32 v132, v143, v142
	v_max3_f32 v162, v162, v163, v164
	v_max3_f32 v130, v130, v131, v132
	ds_bpermute_b32 v163, v171, v162
	ds_bpermute_b32 v131, v171, v130
	s_waitcnt lgkmcnt(0)
	s_waitcnt lgkmcnt(0)
	v_max_f32_e32 v162, v162, v163
	v_max_f32_e32 v130, v130, v131
	ds_bpermute_b32 v163, v199, v162
	ds_bpermute_b32 v131, v199, v130
	s_waitcnt lgkmcnt(0)
	s_waitcnt lgkmcnt(0)
	v_max3_f32 v167, v203, v162, v163
	v_max3_f32 v135, v185, v130, v131
	v_sub_f32_e32 v166, v209, v167
	v_sub_f32_e32 v134, v141, v135
	v_mul_f32_e32 v166, 0x3fb8aa3b, v166
	v_mul_f32_e32 v134, 0x3fb8aa3b, v134
	v_exp_f32_e32 v168, v166
	v_exp_f32_e32 v136, v134
	v_sub_f32_e32 v166, v207, v167
	v_sub_f32_e32 v134, v139, v135
	v_mul_f32_e32 v166, 0x3fb8aa3b, v166
	v_mul_f32_e32 v134, 0x3fb8aa3b, v134
	v_sub_f32_e32 v163, v208, v167
	v_sub_f32_e32 v131, v140, v135
	v_exp_f32_e32 v169, v166
	v_exp_f32_e32 v137, v134
	v_sub_f32_e32 v166, v211, v167
	v_sub_f32_e32 v134, v143, v135
	v_mul_f32_e32 v163, 0x3fb8aa3b, v163
	v_mul_f32_e32 v131, 0x3fb8aa3b, v131
	v_sub_f32_e32 v165, v206, v167
	v_sub_f32_e32 v133, v138, v135
	v_mul_f32_e32 v166, 0x3fb8aa3b, v166
	v_mul_f32_e32 v134, 0x3fb8aa3b, v134
	v_sub_f32_e32 v162, v203, v167
	v_exp_f32_e32 v131, v131
	v_exp_f32_e32 v163, v163
	v_mul_f32_e32 v133, 0x3fb8aa3b, v133
	v_mul_f32_e32 v165, 0x3fb8aa3b, v165
	v_exp_f32_e32 v138, v134
	v_exp_f32_e32 v203, v166
	v_sub_f32_e32 v134, v142, v135
	v_sub_f32_e32 v166, v210, v167
	v_exp_f32_e32 v133, v133
	v_exp_f32_e32 v165, v165
	v_mul_f32_e32 v134, 0x3fb8aa3b, v134
	v_mul_f32_e32 v166, 0x3fb8aa3b, v166
	v_exp_f32_e32 v139, v134
	v_exp_f32_e32 v206, v166
	v_sub_f32_e32 v134, v145, v135
	v_sub_f32_e32 v166, v212, v167
	v_mul_f32_e32 v134, 0x3fb8aa3b, v134
	v_mul_f32_e32 v166, 0x3fb8aa3b, v166
	v_sub_f32_e32 v130, v185, v135
	v_add_f32_e32 v164, 0, v163
	v_add_f32_e32 v132, 0, v131
	v_exp_f32_e32 v207, v166
	v_exp_f32_e32 v140, v134
	v_sub_f32_e32 v166, v189, v167
	v_sub_f32_e32 v134, v144, v135
	v_mul_f32_e32 v162, 0x3fb8aa3b, v162
	v_mul_f32_e32 v130, 0x3fb8aa3b, v130
	v_add_f32_e32 v164, v165, v164
	v_add_f32_e32 v132, v133, v132
	v_mul_f32_e32 v166, 0x3fb8aa3b, v166
	v_mul_f32_e32 v134, 0x3fb8aa3b, v134
	v_add_f32_e32 v164, v168, v164
	v_add_f32_e32 v132, v136, v132
	v_exp_f32_e32 v189, v166
	v_exp_f32_e32 v141, v134
	v_exp_f32_e32 v166, v162
	v_exp_f32_e32 v134, v130
	v_add_f32_e32 v164, v169, v164
	v_add_f32_e32 v132, v137, v132
	v_add_f32_e32 v164, v203, v164
	v_add_f32_e32 v132, v138, v132
	v_add_f32_e32 v164, v206, v164
	v_add_f32_e32 v132, v139, v132
	v_add_f32_e32 v164, v207, v164
	v_add_f32_e32 v132, v140, v132
	v_pk_mul_f32 v[92:93], v[92:93], v[166:167] op_sel_hi:[1,0]
	v_pk_mul_f32 v[32:33], v[32:33], v[134:135] op_sel_hi:[1,0]
	v_pk_mul_f32 v[90:91], v[90:91], v[166:167] op_sel_hi:[1,0]
	v_pk_mul_f32 v[30:31], v[30:31], v[134:135] op_sel_hi:[1,0]
	v_pk_mul_f32 v[76:77], v[76:77], v[166:167] op_sel_hi:[1,0]
	v_pk_mul_f32 v[28:29], v[28:29], v[134:135] op_sel_hi:[1,0]
	v_pk_mul_f32 v[74:75], v[74:75], v[166:167] op_sel_hi:[1,0]
	v_pk_mul_f32 v[26:27], v[26:27], v[134:135] op_sel_hi:[1,0]
	v_pk_mul_f32 v[72:73], v[72:73], v[166:167] op_sel_hi:[1,0]
	v_pk_mul_f32 v[24:25], v[24:25], v[134:135] op_sel_hi:[1,0]
	v_pk_mul_f32 v[70:71], v[70:71], v[166:167] op_sel_hi:[1,0]
	v_pk_mul_f32 v[22:23], v[22:23], v[134:135] op_sel_hi:[1,0]
	v_pk_mul_f32 v[64:65], v[64:65], v[166:167] op_sel_hi:[1,0]
	v_pk_mul_f32 v[20:21], v[20:21], v[134:135] op_sel_hi:[1,0]
	v_pk_mul_f32 v[62:63], v[62:63], v[166:167] op_sel_hi:[1,0]
	v_pk_mul_f32 v[18:19], v[18:19], v[134:135] op_sel_hi:[1,0]
	v_pk_mul_f32 v[48:49], v[48:49], v[166:167] op_sel_hi:[1,0]
	v_pk_mul_f32 v[16:17], v[16:17], v[134:135] op_sel_hi:[1,0]
	v_pk_mul_f32 v[46:47], v[46:47], v[166:167] op_sel_hi:[1,0]
	v_pk_mul_f32 v[14:15], v[14:15], v[134:135] op_sel_hi:[1,0]
	v_pk_mul_f32 v[44:45], v[44:45], v[166:167] op_sel_hi:[1,0]
	v_pk_mul_f32 v[12:13], v[12:13], v[134:135] op_sel_hi:[1,0]
	v_pk_mul_f32 v[42:43], v[42:43], v[166:167] op_sel_hi:[1,0]
	v_pk_mul_f32 v[10:11], v[10:11], v[134:135] op_sel_hi:[1,0]
	v_pk_mul_f32 v[40:41], v[40:41], v[166:167] op_sel_hi:[1,0]
	v_pk_mul_f32 v[8:9], v[8:9], v[134:135] op_sel_hi:[1,0]
	v_pk_mul_f32 v[38:39], v[38:39], v[166:167] op_sel_hi:[1,0]
	v_pk_mul_f32 v[6:7], v[6:7], v[134:135] op_sel_hi:[1,0]
	v_pk_mul_f32 v[36:37], v[36:37], v[166:167] op_sel_hi:[1,0]
	v_pk_mul_f32 v[4:5], v[4:5], v[134:135] op_sel_hi:[1,0]
	v_pk_mul_f32 v[34:35], v[34:35], v[166:167] op_sel_hi:[1,0]
	v_pk_mul_f32 v[2:3], v[2:3], v[134:135] op_sel_hi:[1,0]
	v_add_f32_e32 v208, v189, v164
	v_add_f32_e32 v142, v141, v132
	v_cvt_pk_bf16_f32 v162, v163, v165
	v_cvt_pk_bf16_f32 v130, v131, v133
	v_cvt_pk_bf16_f32 v163, v168, v169
	v_cvt_pk_bf16_f32 v131, v136, v137
	v_cvt_pk_bf16_f32 v164, v203, v206
	v_cvt_pk_bf16_f32 v132, v138, v139
	v_cvt_pk_bf16_f32 v165, v207, v189
	v_cvt_pk_bf16_f32 v133, v140, v141
	v_fmac_f32_e32 v208, v201, v166
	v_fmac_f32_e32 v142, v175, v134
	v_mfma_f32_16x16x32_bf16 v[90:93], v[126:129], v[162:165], v[90:93]
	v_mfma_f32_16x16x32_bf16 v[30:33], v[126:129], v[130:133], v[30:33]
	v_mov_b32_e32 v201, v208
	v_mov_b32_e32 v175, v142
	v_mov_b32_e32 v203, v167
	v_mov_b32_e32 v185, v135
	v_mfma_f32_16x16x32_bf16 v[74:77], v[122:125], v[162:165], v[74:77]
	v_mfma_f32_16x16x32_bf16 v[26:29], v[122:125], v[130:133], v[26:29]
	v_mfma_f32_16x16x32_bf16 v[70:73], v[118:121], v[162:165], v[70:73]
	v_mfma_f32_16x16x32_bf16 v[22:25], v[118:121], v[130:133], v[22:25]
	v_mfma_f32_16x16x32_bf16 v[62:65], v[114:117], v[162:165], v[62:65]
	v_mfma_f32_16x16x32_bf16 v[18:21], v[114:117], v[130:133], v[18:21]
	v_mfma_f32_16x16x32_bf16 v[46:49], v[110:113], v[162:165], v[46:49]
	v_mfma_f32_16x16x32_bf16 v[14:17], v[110:113], v[130:133], v[14:17]
	v_mfma_f32_16x16x32_bf16 v[42:45], v[106:109], v[162:165], v[42:45]
	v_mfma_f32_16x16x32_bf16 v[10:13], v[106:109], v[130:133], v[10:13]
	v_mfma_f32_16x16x32_bf16 v[38:41], v[102:105], v[162:165], v[38:41]
	v_mfma_f32_16x16x32_bf16 v[6:9], v[102:105], v[130:133], v[6:9]
	v_mfma_f32_16x16x32_bf16 v[34:37], v[98:101], v[162:165], v[34:37]
	v_mfma_f32_16x16x32_bf16 v[2:5], v[98:101], v[130:133], v[2:5]
	s_branch .LBB0_285
